# v54 + MoE table rebuild skipped in phases 10/11/19/20 + next-unit gather indices prefetched at unit start (no vmcnt(0) drain in the last K-iteration)
# speedup vs baseline: 1.0024x; 1.0024x over previous
.LBB0_1746:
	v_lshl_add_u64 v[200:201], v[0:1], 0, s[24:25]
	v_mov_b32_e32 v0, 0
	v_add_u32_e32 v214, -1, v193
	s_cmp_lg_u64 s[6:7], 0
	s_cbranch_scc0 .Lgpf_a
	v_mov_b32_e32 v250, v209
	s_nop 0
	v_ashrrev_i32_e32 v242, 31, v250
	v_lshrrev_b32_e32 v242, 26, v242
	v_lshlrev_b32_e32 v244, 4, v250
	v_add_u32_e32 v242, v250, v242
	v_bfe_i32 v250, v250, 27, 1
	v_lshrrev_b32_e32 v250, 22, v250
	v_add_u32_e32 v250, v244, v250
	v_and_b32_e32 v250, 0xfffffc00, v250
	v_sub_u32_e32 v250, v244, v250
	v_add_u32_e32 v244, 0x2000, v244
	v_ashrrev_i32_e32 v245, 31, v244
	v_lshrrev_b32_e32 v245, 22, v245
	v_add_u32_e32 v245, v244, v245
	v_ashrrev_i32_e32 v253, 10, v245
	v_mul_i32_i24_e32 v245, 0x400, v253
	v_ashrrev_i32_e32 v251, 6, v242
	v_lshrrev_b32_e32 v242, 4, v250
	v_sub_u32_e32 v244, v244, v245
	v_bitop3_b32 v250, v242, v250, 32 bitop3:0x6c
	v_lshrrev_b32_e32 v245, 4, v244
	v_ashrrev_i32_e32 v243, 31, v250
	v_bitop3_b32 v254, v245, v244, 32 bitop3:0x6c
	v_lshrrev_b32_e32 v243, 26, v243
	v_ashrrev_i32_e32 v245, 31, v254
	v_lshlrev_b32_e32 v242, 3, v251
	v_add_u32_e32 v252, v250, v243
	v_lshrrev_b32_e32 v245, 26, v245
	v_and_b32_e32 v242, -16, v242
	v_ashrrev_i32_e32 v243, 6, v252
	v_lshlrev_b32_e32 v244, 3, v253
	v_add_u32_e32 v255, v254, v245
	v_add_u32_e32 v246, v243, v242
	v_and_b32_e32 v244, -16, v244
	v_ashrrev_i32_e32 v245, 6, v255
	v_min_i32_e32 v242, v246, v214
	v_add_u32_e32 v248, v245, v244
	v_add_u32_e32 v246, 0x80, v246
	v_min_i32_e32 v244, v248, v214
	v_min_i32_e32 v246, v246, v214
	v_add_u32_e32 v248, 0x80, v248
	v_ashrrev_i32_e32 v243, 31, v242
	v_ashrrev_i32_e32 v245, 31, v244
	v_ashrrev_i32_e32 v247, 31, v246
	v_min_i32_e32 v248, v248, v214
	v_lshl_add_u64 v[242:243], v[242:243], 2, v[190:191]
	v_lshl_add_u64 v[244:245], v[244:245], 2, v[190:191]
	v_lshl_add_u64 v[246:247], v[246:247], 2, v[190:191]
	v_ashrrev_i32_e32 v249, 31, v248
	v_lshl_add_u64 v[248:249], v[248:249], 2, v[190:191]
	global_load_dword v242, v[242:243], off
	s_nop 0
	global_load_dword v244, v[244:245], off
	s_nop 0
	global_load_dword v245, v[246:247], off
	s_nop 0
	global_load_dword v246, v[248:249], off
	v_and_b32_e32 v249, 0xc0, v252
	v_sub_u32_e32 v250, v250, v249
	v_lshlrev_b32_e32 v247, 5, v251
	v_ashrrev_i16_sdwa v250, v199, sext(v250) dst_sel:DWORD dst_unused:UNUSED_PAD src0_sel:DWORD src1_sel:BYTE_0
	v_and_b32_e32 v247, 32, v247
	v_bfe_i32 v250, v250, 0, 16
	v_and_b32_e32 v249, 0xc0, v255
	v_add_lshl_u32 v250, v247, v250, 1
	v_sub_u32_e32 v247, v254, v249
	v_lshlrev_b32_e32 v248, 5, v253
	v_ashrrev_i16_sdwa v247, v199, sext(v247) dst_sel:DWORD dst_unused:UNUSED_PAD src0_sel:DWORD src1_sel:BYTE_0
	v_and_b32_e32 v248, 32, v248
	v_bfe_i32 v247, v247, 0, 16
	v_add_lshl_u32 v247, v248, v247, 1
	v_mov_b32_e32 v243, v181
.Lgpf_a:
	v_lshl_add_u64 v[202:203], v[2:3], 0, s[28:29]
	s_mov_b32 s51, -2
	v_mov_b32_e32 v180, v4
	v_mov_b32_e32 v1, v0
	v_mov_b32_e32 v2, v0
	v_mov_b32_e32 v3, v0
	v_mov_b32_e32 v8, v0
	v_mov_b32_e32 v9, v0
	v_mov_b32_e32 v10, v0
	v_mov_b32_e32 v11, v0
	v_mov_b32_e32 v16, v0
	v_mov_b32_e32 v17, v0
	v_mov_b32_e32 v18, v0
	v_mov_b32_e32 v19, v0
	v_mov_b32_e32 v24, v0
	v_mov_b32_e32 v25, v0
	v_mov_b32_e32 v26, v0
	v_mov_b32_e32 v27, v0
	v_mov_b32_e32 v32, v0
	v_mov_b32_e32 v33, v0
	v_mov_b32_e32 v34, v0
	v_mov_b32_e32 v35, v0
	v_mov_b32_e32 v40, v0
	v_mov_b32_e32 v41, v0
	v_mov_b32_e32 v42, v0
	v_mov_b32_e32 v43, v0
	v_mov_b32_e32 v48, v0
	v_mov_b32_e32 v49, v0
	v_mov_b32_e32 v50, v0
	v_mov_b32_e32 v51, v0
	v_mov_b32_e32 v56, v0
	v_mov_b32_e32 v57, v0
	v_mov_b32_e32 v58, v0
	v_mov_b32_e32 v59, v0
	v_mov_b32_e32 v4, v0
	v_mov_b32_e32 v5, v0
	v_mov_b32_e32 v6, v0
	v_mov_b32_e32 v7, v0
	v_mov_b32_e32 v12, v0
	v_mov_b32_e32 v13, v0
	v_mov_b32_e32 v14, v0
	v_mov_b32_e32 v15, v0
	v_mov_b32_e32 v20, v0
	v_mov_b32_e32 v21, v0
	v_mov_b32_e32 v22, v0
	v_mov_b32_e32 v23, v0
	v_mov_b32_e32 v28, v0
	v_mov_b32_e32 v29, v0
	v_mov_b32_e32 v30, v0
	v_mov_b32_e32 v31, v0
	v_mov_b32_e32 v36, v0
	v_mov_b32_e32 v37, v0
	v_mov_b32_e32 v38, v0
	v_mov_b32_e32 v39, v0
	v_mov_b32_e32 v44, v0
	v_mov_b32_e32 v45, v0
	v_mov_b32_e32 v46, v0
	v_mov_b32_e32 v47, v0
	v_mov_b32_e32 v52, v0
	v_mov_b32_e32 v53, v0
	v_mov_b32_e32 v54, v0
	v_mov_b32_e32 v55, v0
	v_mov_b32_e32 v60, v0
	v_mov_b32_e32 v61, v0
	v_mov_b32_e32 v62, v0
	v_mov_b32_e32 v63, v0
	v_mov_b32_e32 v64, v0
	v_mov_b32_e32 v65, v0
	v_mov_b32_e32 v66, v0
	v_mov_b32_e32 v67, v0
	v_mov_b32_e32 v72, v0
	v_mov_b32_e32 v73, v0
	v_mov_b32_e32 v74, v0
	v_mov_b32_e32 v75, v0
	v_mov_b32_e32 v80, v0
	v_mov_b32_e32 v81, v0
	v_mov_b32_e32 v82, v0
	v_mov_b32_e32 v83, v0
	v_mov_b32_e32 v88, v0
	v_mov_b32_e32 v89, v0
	v_mov_b32_e32 v90, v0
	v_mov_b32_e32 v91, v0
	v_mov_b32_e32 v96, v0
	v_mov_b32_e32 v97, v0
	v_mov_b32_e32 v98, v0
	v_mov_b32_e32 v99, v0
	v_mov_b32_e32 v104, v0
	v_mov_b32_e32 v105, v0
	v_mov_b32_e32 v106, v0
	v_mov_b32_e32 v107, v0
	v_mov_b32_e32 v112, v0
	v_mov_b32_e32 v113, v0
	v_mov_b32_e32 v114, v0
	v_mov_b32_e32 v115, v0
	v_mov_b32_e32 v120, v0
	v_mov_b32_e32 v121, v0
	v_mov_b32_e32 v122, v0
	v_mov_b32_e32 v123, v0
	v_mov_b32_e32 v68, v0
	v_mov_b32_e32 v69, v0
	v_mov_b32_e32 v70, v0
	v_mov_b32_e32 v71, v0
	v_mov_b32_e32 v76, v0
	v_mov_b32_e32 v77, v0
	v_mov_b32_e32 v78, v0
	v_mov_b32_e32 v79, v0
	v_mov_b32_e32 v84, v0
	v_mov_b32_e32 v85, v0
	v_mov_b32_e32 v86, v0
	v_mov_b32_e32 v87, v0
	v_mov_b32_e32 v92, v0
	v_mov_b32_e32 v93, v0
	v_mov_b32_e32 v94, v0
	v_mov_b32_e32 v95, v0
	v_mov_b32_e32 v100, v0
	v_mov_b32_e32 v101, v0
	v_mov_b32_e32 v102, v0
	v_mov_b32_e32 v103, v0
	v_mov_b32_e32 v108, v0
	v_mov_b32_e32 v109, v0
	v_mov_b32_e32 v110, v0
	v_mov_b32_e32 v111, v0
	v_mov_b32_e32 v116, v0
	v_mov_b32_e32 v117, v0
	v_mov_b32_e32 v118, v0
	v_mov_b32_e32 v119, v0
	v_mov_b32_e32 v124, v0
	v_mov_b32_e32 v125, v0
	v_mov_b32_e32 v126, v0
	v_mov_b32_e32 v127, v0
	s_branch .LBB0_1749
.LBB0_1747:
	v_mov_b32_e32 v180, v209
	s_nop 0
	v_ashrrev_i32_e32 v182, 31, v180
	v_lshrrev_b32_e32 v182, 26, v182
	v_lshlrev_b32_e32 v184, 4, v180
	v_add_u32_e32 v182, v180, v182
	v_bfe_i32 v180, v180, 27, 1
	v_lshrrev_b32_e32 v180, 22, v180
	v_add_u32_e32 v180, v184, v180
	v_and_b32_e32 v180, 0xfffffc00, v180
	v_sub_u32_e32 v180, v184, v180
	v_add_u32_e32 v184, 0x2000, v184
	v_ashrrev_i32_e32 v185, 31, v184
	v_lshrrev_b32_e32 v185, 22, v185
	v_add_u32_e32 v185, v184, v185
	v_ashrrev_i32_e32 v215, 10, v185
	v_mul_i32_i24_e32 v185, 0x400, v215
	v_ashrrev_i32_e32 v206, 6, v182
	v_lshrrev_b32_e32 v182, 4, v180
	v_sub_u32_e32 v184, v184, v185
	v_bitop3_b32 v180, v182, v180, 32 bitop3:0x6c
	v_lshrrev_b32_e32 v185, 4, v184
	v_ashrrev_i32_e32 v183, 31, v180
	v_bitop3_b32 v216, v185, v184, 32 bitop3:0x6c
	v_lshrrev_b32_e32 v183, 26, v183
	v_ashrrev_i32_e32 v185, 31, v216
	v_lshlrev_b32_e32 v182, 3, v206
	v_add_u32_e32 v207, v180, v183
	v_lshrrev_b32_e32 v185, 26, v185
	v_and_b32_e32 v182, -16, v182
	v_ashrrev_i32_e32 v183, 6, v207
	v_lshlrev_b32_e32 v184, 3, v215
	v_add_u32_e32 v217, v216, v185
	v_add_u32_e32 v186, v183, v182
	v_and_b32_e32 v184, -16, v184
	v_ashrrev_i32_e32 v185, 6, v217
	v_min_i32_e32 v182, v186, v214
	v_add_u32_e32 v204, v185, v184
	v_add_u32_e32 v186, 0x80, v186
	v_min_i32_e32 v184, v204, v214
	v_min_i32_e32 v186, v186, v214
	v_add_u32_e32 v204, 0x80, v204
	v_ashrrev_i32_e32 v183, 31, v182
	v_ashrrev_i32_e32 v185, 31, v184
	v_ashrrev_i32_e32 v187, 31, v186
	v_min_i32_e32 v204, v204, v214
	v_lshl_add_u64 v[182:183], v[182:183], 2, v[190:191]
	v_lshl_add_u64 v[184:185], v[184:185], 2, v[190:191]
	v_lshl_add_u64 v[186:187], v[186:187], 2, v[190:191]
	v_ashrrev_i32_e32 v205, 31, v204
	v_lshl_add_u64 v[204:205], v[204:205], 2, v[190:191]
	v_mov_b32_e32 v182, v242
	s_nop 0
	v_mov_b32_e32 v184, v244
	s_nop 0
	v_mov_b32_e32 v185, v245
	s_nop 0
	v_mov_b32_e32 v186, v246
	v_and_b32_e32 v205, 0xc0, v207
	v_sub_u32_e32 v180, v180, v205
	v_lshlrev_b32_e32 v187, 5, v206
	v_ashrrev_i16_sdwa v180, v199, sext(v180) dst_sel:DWORD dst_unused:UNUSED_PAD src0_sel:DWORD src1_sel:BYTE_0
	v_and_b32_e32 v187, 32, v187
	v_bfe_i32 v180, v180, 0, 16
	v_and_b32_e32 v205, 0xc0, v217
	v_add_lshl_u32 v180, v187, v180, 1
	v_sub_u32_e32 v187, v216, v205
	v_lshlrev_b32_e32 v204, 5, v215
	v_ashrrev_i16_sdwa v187, v199, sext(v187) dst_sel:DWORD dst_unused:UNUSED_PAD src0_sel:DWORD src1_sel:BYTE_0
	v_and_b32_e32 v204, 32, v204
	v_bfe_i32 v187, v187, 0, 16
	v_add_lshl_u32 v187, v204, v187, 1
	v_mov_b32_e32 v183, v181
	v_lshl_add_u32 v206, v182, 12, v180
	v_lshl_add_u32 v184, v184, 12, v187
	v_lshl_add_u32 v180, v185, 12, v180
	v_lshl_add_u32 v182, v186, 12, v187
	v_mov_b64_e32 v[204:205], v[180:181]
	v_mov_b32_e32 v186, v180
	v_mov_b32_e32 v180, v206

.LBB0_1806:
	s_cmp_gt_i32 s40, 10
	s_cselect_b64 s[4:5], -1, 0
	s_cmp_lt_i32 s41, 11
	s_cselect_b64 s[6:7], -1, 0
	s_or_b64 s[4:5], s[4:5], s[6:7]
	s_and_b64 vcc, exec, s[4:5]
	s_cbranch_vccnz .LBB0_1887
	v_mbcnt_lo_u32_b32 v0, -1, 0
	v_mbcnt_hi_u32_b32 v12, -1, v0
	v_add_u32_e32 v13, s63, v12
	s_mov_b64 s[4:5], s[0:1]
	v_cmp_eq_u32_e32 vcc, 0, v13
	s_waitcnt vmcnt(0) lgkmcnt(0)
	s_barrier
	s_cmp_le_i32 s40, 9
	s_cselect_b64 s[6:7], 0, -1
	s_and_b64 vcc, vcc, s[6:7]
	s_and_saveexec_b64 s[6:7], vcc
	s_cbranch_execz .LBB0_1809
	s_load_dwordx2 s[8:9], s[4:5], 0x178
	v_mov_b32_e32 v0, 0
	s_add_i32 s12, 0, 0x221e0
	v_mov_b32_e32 v1, s12
	s_add_i32 s10, 0, 0x220a0
	s_waitcnt lgkmcnt(0)
	global_load_dwordx4 v[14:17], v0, s[8:9]
	global_load_dwordx4 v[18:21], v0, s[8:9] offset:16
	global_load_dwordx4 v[8:11], v0, s[8:9] offset:32
	global_load_dwordx4 v[4:7], v0, s[8:9] offset:48
	s_add_i32 s17, 0, 0x221f0
	global_load_dwordx4 v[22:25], v0, s[8:9] offset:80
	global_load_dwordx4 v[26:29], v0, s[8:9] offset:64
	s_add_i32 s3, 0, 0x22000
	s_add_i32 s15, 0, 0x220b0
	v_mov_b32_e32 v2, s10
	v_mov_b32_e32 v30, s17
	s_add_i32 s11, 0, 0x22140
	v_mov_b32_e32 v32, s3
	v_mov_b32_e32 v3, s15
	s_add_i32 s13, 0, 0x2200c
	v_mov_b32_e32 v33, s11
	v_mov_b32_e32 v34, s13
	s_add_i32 s14, 0, 0x22014
	s_add_i32 s16, 0, 0x22150
	v_mov_b32_e32 v35, s14
	s_add_i32 s18, 0, 0x2201c
	v_mov_b32_e32 v36, s16
	v_mov_b32_e32 v37, s18
	s_add_i32 s3, 0, 0x22024
	s_waitcnt vmcnt(5)
	v_add_u32_e32 v31, 0xff, v15
	v_add_u32_e32 v38, 0xff, v14
	v_add_u32_e32 v39, 0xff, v17
	v_add_u32_e32 v40, 0xff, v16
	ds_write_b128 v1, v[14:17]
	v_ashrrev_i32_e32 v14, 8, v38
	v_ashrrev_i32_e32 v15, 8, v31
	s_waitcnt vmcnt(4)
	v_add_u32_e32 v1, 0xff, v19
	v_add_u32_e32 v41, 0xff, v18
	v_add_u32_e32 v42, 0xff, v21
	v_add_u32_e32 v43, 0xff, v20
	v_and_b32_e32 v45, 0xffffff00, v38
	v_and_b32_e32 v38, 0xffffff00, v31
	v_ashrrev_i32_e32 v17, 8, v39
	v_ashrrev_i32_e32 v16, 8, v40
	v_add_u32_e32 v48, v15, v14
	ds_write_b128 v30, v[18:21]
	v_and_b32_e32 v46, 0xffffff00, v40
	v_and_b32_e32 v40, 0xffffff00, v41
	v_ashrrev_i32_e32 v19, 8, v1
	v_ashrrev_i32_e32 v18, 8, v41
	v_and_b32_e32 v41, 0xffffff00, v1
	v_ashrrev_i32_e32 v21, 8, v42
	v_ashrrev_i32_e32 v20, 8, v43
	v_add_u32_e32 v38, v38, v45
	v_lshlrev_b32_e32 v1, 3, v14
	ds_write_b128 v2, v[14:17]
	ds_write_b128 v3, v[18:21]
	v_lshlrev_b32_e32 v2, 3, v48
	v_add_u32_e32 v15, v16, v48
	v_and_b32_e32 v39, 0xffffff00, v39
	v_add_u32_e32 v3, v46, v38
	ds_write_b96 v32, v[0:2]
	v_mov_b32_e32 v1, v45
	v_mov_b32_e32 v2, v38
	v_add_u32_e32 v16, v17, v15
	v_add_u32_e32 v14, v39, v3
	v_lshlrev_b32_e32 v17, 3, v15
	ds_write_b128 v33, v[0:3]
	v_lshlrev_b32_e32 v1, 3, v16
	v_add_u32_e32 v2, v18, v16
	v_add_u32_e32 v15, v40, v14
	ds_write2_b32 v34, v17, v1 offset1:1
	v_add_u32_e32 v1, v19, v2
	s_waitcnt vmcnt(3)
	v_add_u32_e32 v30, 0xff, v8
	v_and_b32_e32 v47, 0xffffff00, v43
	v_add_u32_e32 v16, v41, v15
	v_lshlrev_b32_e32 v2, 3, v2
	v_lshlrev_b32_e32 v3, 3, v1
	v_add_u32_e32 v1, v20, v1
	v_add_u32_e32 v44, 0xff, v9
	v_and_b32_e32 v43, 0xffffff00, v30
	v_ashrrev_i32_e32 v30, 8, v30
	v_add_u32_e32 v17, v47, v16
	ds_write2_b32 v35, v2, v3 offset1:1
	ds_write_b128 v36, v[14:17]
	v_add_u32_e32 v2, v21, v1
	v_ashrrev_i32_e32 v31, 8, v44
	v_lshlrev_b32_e32 v1, 3, v1
	v_lshlrev_b32_e32 v3, 3, v2
	v_add_u32_e32 v2, v30, v2
	v_and_b32_e32 v42, 0xffffff00, v42
	ds_write2_b32 v37, v1, v3 offset1:1
	v_add_u32_e32 v1, v31, v2
	v_add_u32_e32 v14, v42, v17
	v_lshlrev_b32_e32 v2, 3, v2
	v_lshlrev_b32_e32 v3, 3, v1
	v_mov_b32_e32 v17, s3
	v_and_b32_e32 v44, 0xffffff00, v44
	v_add_u32_e32 v15, v43, v14
	ds_write2_b32 v17, v2, v3 offset1:1
	v_add_u32_e32 v2, 0xff, v11
	v_add_u32_e32 v3, 0xff, v10
	s_add_i32 s3, 0, 0x220c0
	v_add_u32_e32 v16, v44, v15
	v_and_b32_e32 v17, 0xffffff00, v3
	v_ashrrev_i32_e32 v33, 8, v2
	v_ashrrev_i32_e32 v32, 8, v3
	v_mov_b32_e32 v3, s3
	s_add_i32 s3, 0, 0x22160
	v_add_u32_e32 v17, v17, v16
	ds_write_b128 v3, v[30:33]
	v_mov_b32_e32 v3, s3
	s_add_i32 s3, 0, 0x22200
	ds_write_b128 v3, v[14:17]
	v_mov_b32_e32 v3, s3
	v_and_b32_e32 v2, 0xffffff00, v2
	v_add_u32_e32 v1, v32, v1
	ds_write_b128 v3, v[8:11]
	v_add_u32_e32 v8, v2, v17
	v_add_u32_e32 v2, v33, v1
	s_add_i32 s3, 0, 0x2202c
	v_lshlrev_b32_e32 v1, 3, v1
	v_lshlrev_b32_e32 v3, 3, v2
	v_mov_b32_e32 v9, s3
	ds_write2_b32 v9, v1, v3 offset1:1
	s_waitcnt vmcnt(2)
	v_add_u32_e32 v3, 0xff, v4
	v_add_u32_e32 v1, 0xff, v5
	v_and_b32_e32 v9, 0xffffff00, v3
	v_add_u32_e32 v9, v9, v8
	v_ashrrev_i32_e32 v15, 8, v1
	v_ashrrev_i32_e32 v14, 8, v3
	v_and_b32_e32 v1, 0xffffff00, v1
	v_add_u32_e32 v10, v1, v9
	v_add_u32_e32 v1, v14, v2
	v_add_u32_e32 v3, v15, v1
	s_add_i32 s3, 0, 0x22034
	v_lshlrev_b32_e32 v1, 3, v1
	v_lshlrev_b32_e32 v2, 3, v3
	v_mov_b32_e32 v11, s3
	ds_write2_b32 v11, v1, v2 offset1:1
	v_add_u32_e32 v1, 0xff, v7
	v_add_u32_e32 v2, 0xff, v6
	s_add_i32 s3, 0, 0x220d0
	v_and_b32_e32 v11, 0xffffff00, v2
	v_ashrrev_i32_e32 v17, 8, v1
	v_ashrrev_i32_e32 v16, 8, v2
	v_mov_b32_e32 v2, s3
	s_add_i32 s3, 0, 0x22170
	v_add_u32_e32 v11, v11, v10
	ds_write_b128 v2, v[14:17]
	v_mov_b32_e32 v2, s3
	s_add_i32 s3, 0, 0x22210
	ds_write_b128 v2, v[8:11]
	v_mov_b32_e32 v2, s3
	v_and_b32_e32 v1, 0xffffff00, v1
	ds_write_b128 v2, v[4:7]
	v_add_u32_e32 v2, v1, v11
	v_add_u32_e32 v1, v16, v3
	v_add_u32_e32 v5, v17, v1
	global_load_dwordx4 v[6:9], v0, s[8:9] offset:112
	global_load_dwordx4 v[14:17], v0, s[8:9] offset:96
	s_add_i32 s3, 0, 0x2203c
	v_lshlrev_b32_e32 v1, 3, v1
	v_lshlrev_b32_e32 v3, 3, v5
	v_mov_b32_e32 v4, s3
	ds_write2_b32 v4, v1, v3 offset1:1
	s_waitcnt vmcnt(2)
	v_add_u32_e32 v1, 0xff, v26
	v_add_u32_e32 v0, 0xff, v27
	v_and_b32_e32 v3, 0xffffff00, v1
	v_add_u32_e32 v3, v3, v2
	v_ashrrev_i32_e32 v19, 8, v0
	v_ashrrev_i32_e32 v18, 8, v1
	v_and_b32_e32 v0, 0xffffff00, v0
	v_add_u32_e32 v4, v0, v3
	v_add_u32_e32 v0, v18, v5
	v_add_u32_e32 v1, v19, v0
	s_add_i32 s3, 0, 0x22044
	v_lshlrev_b32_e32 v0, 3, v0
	v_lshlrev_b32_e32 v5, 3, v1
	v_mov_b32_e32 v10, s3
	ds_write2_b32 v10, v0, v5 offset1:1
	v_add_u32_e32 v0, 0xff, v29
	v_add_u32_e32 v10, 0xff, v28
	s_add_i32 s3, 0, 0x220e0
	v_and_b32_e32 v5, 0xffffff00, v10
	v_ashrrev_i32_e32 v21, 8, v0
	v_ashrrev_i32_e32 v20, 8, v10
	v_mov_b32_e32 v10, s3
	s_add_i32 s3, 0, 0x22180
	v_add_u32_e32 v5, v5, v4
	ds_write_b128 v10, v[18:21]
	v_mov_b32_e32 v10, s3
	s_add_i32 s3, 0, 0x22220
	v_add_u32_e32 v1, v20, v1
	ds_write_b128 v10, v[2:5]
	v_mov_b32_e32 v2, s3
	v_add_u32_e32 v3, v21, v1
	s_add_i32 s3, 0, 0x2204c
	ds_write_b128 v2, v[26:29]
	v_lshlrev_b32_e32 v1, 3, v1
	v_lshlrev_b32_e32 v2, 3, v3
	v_mov_b32_e32 v4, s3
	ds_write2_b32 v4, v1, v2 offset1:1
	v_add_u32_e32 v4, 0xff, v22
	v_add_u32_e32 v2, 0xff, v23
	v_ashrrev_i32_e32 v18, 8, v4
	v_ashrrev_i32_e32 v19, 8, v2
	v_add_u32_e32 v3, v18, v3
	v_and_b32_e32 v0, 0xffffff00, v0
	v_and_b32_e32 v1, 0xffffff00, v4
	v_add_u32_e32 v4, v19, v3
	s_add_i32 s3, 0, 0x22054
	v_add_u32_e32 v0, v0, v5
	v_lshlrev_b32_e32 v3, 3, v3
	v_lshlrev_b32_e32 v5, 3, v4
	v_mov_b32_e32 v10, s3
	v_add_u32_e32 v1, v1, v0
	v_and_b32_e32 v2, 0xffffff00, v2
	ds_write2_b32 v10, v3, v5 offset1:1
	v_add_u32_e32 v5, 0xff, v25
	v_add_u32_e32 v10, 0xff, v24
	s_add_i32 s3, 0, 0x220f0
	v_add_u32_e32 v2, v2, v1
	v_and_b32_e32 v3, 0xffffff00, v10
	v_ashrrev_i32_e32 v21, 8, v5
	v_ashrrev_i32_e32 v20, 8, v10
	v_mov_b32_e32 v10, s3
	s_add_i32 s3, 0, 0x22190
	v_add_u32_e32 v3, v3, v2
	ds_write_b128 v10, v[18:21]
	v_mov_b32_e32 v10, s3
	s_add_i32 s3, 0, 0x22230
	ds_write_b128 v10, v[0:3]
	v_mov_b32_e32 v0, s3
	ds_write_b128 v0, v[22:25]
	v_and_b32_e32 v0, 0xffffff00, v5
	v_add_u32_e32 v1, v20, v4
	v_add_u32_e32 v0, v0, v3
	v_add_u32_e32 v3, v21, v1
	s_add_i32 s3, 0, 0x2205c
	v_lshlrev_b32_e32 v1, 3, v1
	v_lshlrev_b32_e32 v2, 3, v3
	v_mov_b32_e32 v4, s3
	ds_write2_b32 v4, v1, v2 offset1:1
	s_waitcnt vmcnt(0)
	v_add_u32_e32 v4, 0xff, v14
	v_add_u32_e32 v2, 0xff, v15
	v_ashrrev_i32_e32 v18, 8, v4
	v_ashrrev_i32_e32 v19, 8, v2
	v_add_u32_e32 v3, v18, v3
	v_and_b32_e32 v1, 0xffffff00, v4
	v_add_u32_e32 v4, v19, v3
	s_add_i32 s3, 0, 0x22064
	v_lshlrev_b32_e32 v3, 3, v3
	v_lshlrev_b32_e32 v5, 3, v4
	v_mov_b32_e32 v10, s3
	v_add_u32_e32 v1, v1, v0
	v_and_b32_e32 v2, 0xffffff00, v2
	ds_write2_b32 v10, v3, v5 offset1:1
	v_add_u32_e32 v5, 0xff, v17
	v_add_u32_e32 v10, 0xff, v16
	s_add_i32 s3, 0, 0x22100
	v_add_u32_e32 v2, v2, v1
	v_and_b32_e32 v3, 0xffffff00, v10
	v_ashrrev_i32_e32 v21, 8, v5
	v_ashrrev_i32_e32 v20, 8, v10
	v_mov_b32_e32 v10, s3
	s_add_i32 s3, 0, 0x221a0
	v_add_u32_e32 v3, v3, v2
	ds_write_b128 v10, v[18:21]
	v_mov_b32_e32 v10, s3
	s_add_i32 s3, 0, 0x22240
	ds_write_b128 v10, v[0:3]
	v_mov_b32_e32 v0, s3
	ds_write_b128 v0, v[14:17]
	v_and_b32_e32 v0, 0xffffff00, v5
	v_add_u32_e32 v1, v20, v4
	v_add_u32_e32 v0, v0, v3
	v_add_u32_e32 v3, v21, v1
	s_add_i32 s3, 0, 0x2206c
	v_lshlrev_b32_e32 v1, 3, v1
	v_lshlrev_b32_e32 v2, 3, v3
	v_mov_b32_e32 v4, s3
	ds_write2_b32 v4, v1, v2 offset1:1
	v_add_u32_e32 v4, 0xff, v6
	v_add_u32_e32 v2, 0xff, v7
	v_ashrrev_i32_e32 v14, 8, v4
	v_ashrrev_i32_e32 v15, 8, v2
	v_add_u32_e32 v3, v14, v3
	v_and_b32_e32 v1, 0xffffff00, v4
	v_add_u32_e32 v4, v15, v3
	s_add_i32 s3, 0, 0x22074
	v_lshlrev_b32_e32 v3, 3, v3
	v_lshlrev_b32_e32 v5, 3, v4
	v_mov_b32_e32 v10, s3
	v_add_u32_e32 v1, v1, v0
	v_and_b32_e32 v2, 0xffffff00, v2
	ds_write2_b32 v10, v3, v5 offset1:1
	v_add_u32_e32 v5, 0xff, v9
	v_add_u32_e32 v10, 0xff, v8
	s_add_i32 s3, 0, 0x22110
	v_add_u32_e32 v2, v2, v1
	v_and_b32_e32 v3, 0xffffff00, v10
	v_ashrrev_i32_e32 v17, 8, v5
	v_ashrrev_i32_e32 v16, 8, v10
	v_mov_b32_e32 v5, s3
	s_add_i32 s3, 0, 0x221b0
	v_add_u32_e32 v3, v3, v2
	ds_write_b128 v5, v[14:17]
	v_mov_b32_e32 v5, s3
	s_add_i32 s3, 0, 0x22250
	ds_write_b128 v5, v[0:3]
	v_mov_b32_e32 v0, s3
	ds_write_b128 v0, v[6:9]
	v_add_u32_e32 v0, v16, v4
	v_add_u32_e32 v1, v17, v0
	s_add_i32 s3, 0, 0x2207c
	v_lshlrev_b32_e32 v0, 3, v0
	v_lshlrev_b32_e32 v1, 3, v1
	v_mov_b32_e32 v2, s3
	ds_write2_b32 v2, v0, v1 offset1:1

.LBB0_1887:
	s_cmp_gt_i32 s40, 11
	s_cselect_b64 s[4:5], -1, 0
	s_cmp_lt_i32 s41, 12
	s_cselect_b64 s[6:7], -1, 0
	s_or_b64 s[4:5], s[4:5], s[6:7]
	s_and_b64 vcc, exec, s[4:5]
	s_cbranch_vccnz .LBB0_1945
	v_mbcnt_lo_u32_b32 v0, -1, 0
	v_mbcnt_hi_u32_b32 v12, -1, v0
	v_add_u32_e32 v13, s63, v12
	s_waitcnt lgkmcnt(0)
	s_mov_b64 s[20:21], s[0:1]
	v_cmp_eq_u32_e32 vcc, 0, v13
	s_waitcnt vmcnt(0)
	s_barrier
	s_cmp_le_i32 s40, 9
	s_cselect_b64 s[4:5], 0, -1
	s_and_b64 vcc, vcc, s[4:5]
	s_and_saveexec_b64 s[4:5], vcc
	s_cbranch_execz .LBB0_1890
	s_load_dwordx2 s[6:7], s[20:21], 0x178
	v_mov_b32_e32 v0, 0
	s_add_i32 s10, 0, 0x221e0
	v_mov_b32_e32 v1, s10
	s_add_i32 s8, 0, 0x220a0
	s_waitcnt lgkmcnt(0)
	global_load_dwordx4 v[14:17], v0, s[6:7]
	global_load_dwordx4 v[18:21], v0, s[6:7] offset:16
	global_load_dwordx4 v[8:11], v0, s[6:7] offset:32
	global_load_dwordx4 v[4:7], v0, s[6:7] offset:48
	s_add_i32 s15, 0, 0x221f0
	global_load_dwordx4 v[22:25], v0, s[6:7] offset:80
	global_load_dwordx4 v[26:29], v0, s[6:7] offset:64
	s_add_i32 s3, 0, 0x22000
	s_add_i32 s13, 0, 0x220b0
	v_mov_b32_e32 v2, s8
	v_mov_b32_e32 v30, s15
	s_add_i32 s9, 0, 0x22140
	v_mov_b32_e32 v32, s3
	v_mov_b32_e32 v3, s13
	s_add_i32 s11, 0, 0x2200c
	v_mov_b32_e32 v33, s9
	v_mov_b32_e32 v34, s11
	s_add_i32 s12, 0, 0x22014
	s_add_i32 s14, 0, 0x22150
	v_mov_b32_e32 v35, s12
	s_add_i32 s16, 0, 0x2201c
	v_mov_b32_e32 v36, s14
	v_mov_b32_e32 v37, s16
	s_add_i32 s3, 0, 0x22024
	s_waitcnt vmcnt(5)
	v_add_u32_e32 v31, 0xff, v15
	v_add_u32_e32 v38, 0xff, v14
	v_add_u32_e32 v39, 0xff, v17
	v_add_u32_e32 v40, 0xff, v16
	ds_write_b128 v1, v[14:17]
	v_ashrrev_i32_e32 v14, 8, v38
	v_ashrrev_i32_e32 v15, 8, v31
	s_waitcnt vmcnt(4)
	v_add_u32_e32 v1, 0xff, v19
	v_add_u32_e32 v41, 0xff, v18
	v_add_u32_e32 v42, 0xff, v21
	v_add_u32_e32 v43, 0xff, v20
	v_and_b32_e32 v45, 0xffffff00, v38
	v_and_b32_e32 v38, 0xffffff00, v31
	v_ashrrev_i32_e32 v17, 8, v39
	v_ashrrev_i32_e32 v16, 8, v40
	v_add_u32_e32 v48, v15, v14
	ds_write_b128 v30, v[18:21]
	v_and_b32_e32 v46, 0xffffff00, v40
	v_and_b32_e32 v40, 0xffffff00, v41
	v_ashrrev_i32_e32 v19, 8, v1
	v_ashrrev_i32_e32 v18, 8, v41
	v_and_b32_e32 v41, 0xffffff00, v1
	v_ashrrev_i32_e32 v21, 8, v42
	v_ashrrev_i32_e32 v20, 8, v43
	v_add_u32_e32 v38, v38, v45
	v_lshlrev_b32_e32 v1, 3, v14
	ds_write_b128 v2, v[14:17]
	ds_write_b128 v3, v[18:21]
	v_lshlrev_b32_e32 v2, 3, v48
	v_add_u32_e32 v15, v16, v48
	v_and_b32_e32 v39, 0xffffff00, v39
	v_add_u32_e32 v3, v46, v38
	ds_write_b96 v32, v[0:2]
	v_mov_b32_e32 v1, v45
	v_mov_b32_e32 v2, v38
	v_add_u32_e32 v16, v17, v15
	v_add_u32_e32 v14, v39, v3
	v_lshlrev_b32_e32 v17, 3, v15
	ds_write_b128 v33, v[0:3]
	v_lshlrev_b32_e32 v1, 3, v16
	v_add_u32_e32 v2, v18, v16
	v_add_u32_e32 v15, v40, v14
	ds_write2_b32 v34, v17, v1 offset1:1
	v_add_u32_e32 v1, v19, v2
	s_waitcnt vmcnt(3)
	v_add_u32_e32 v30, 0xff, v8
	v_and_b32_e32 v47, 0xffffff00, v43
	v_add_u32_e32 v16, v41, v15
	v_lshlrev_b32_e32 v2, 3, v2
	v_lshlrev_b32_e32 v3, 3, v1
	v_add_u32_e32 v1, v20, v1
	v_add_u32_e32 v44, 0xff, v9
	v_and_b32_e32 v43, 0xffffff00, v30
	v_ashrrev_i32_e32 v30, 8, v30
	v_add_u32_e32 v17, v47, v16
	ds_write2_b32 v35, v2, v3 offset1:1
	ds_write_b128 v36, v[14:17]
	v_add_u32_e32 v2, v21, v1
	v_ashrrev_i32_e32 v31, 8, v44
	v_lshlrev_b32_e32 v1, 3, v1
	v_lshlrev_b32_e32 v3, 3, v2
	v_add_u32_e32 v2, v30, v2
	v_and_b32_e32 v42, 0xffffff00, v42
	ds_write2_b32 v37, v1, v3 offset1:1
	v_add_u32_e32 v1, v31, v2
	v_add_u32_e32 v14, v42, v17
	v_lshlrev_b32_e32 v2, 3, v2
	v_lshlrev_b32_e32 v3, 3, v1
	v_mov_b32_e32 v17, s3
	v_and_b32_e32 v44, 0xffffff00, v44
	v_add_u32_e32 v15, v43, v14
	ds_write2_b32 v17, v2, v3 offset1:1
	v_add_u32_e32 v2, 0xff, v11
	v_add_u32_e32 v3, 0xff, v10
	s_add_i32 s3, 0, 0x220c0
	v_add_u32_e32 v16, v44, v15
	v_and_b32_e32 v17, 0xffffff00, v3
	v_ashrrev_i32_e32 v33, 8, v2
	v_ashrrev_i32_e32 v32, 8, v3
	v_mov_b32_e32 v3, s3
	s_add_i32 s3, 0, 0x22160
	v_add_u32_e32 v17, v17, v16
	ds_write_b128 v3, v[30:33]
	v_mov_b32_e32 v3, s3
	s_add_i32 s3, 0, 0x22200
	ds_write_b128 v3, v[14:17]
	v_mov_b32_e32 v3, s3
	v_and_b32_e32 v2, 0xffffff00, v2
	v_add_u32_e32 v1, v32, v1
	ds_write_b128 v3, v[8:11]
	v_add_u32_e32 v8, v2, v17
	v_add_u32_e32 v2, v33, v1
	s_add_i32 s3, 0, 0x2202c
	v_lshlrev_b32_e32 v1, 3, v1
	v_lshlrev_b32_e32 v3, 3, v2
	v_mov_b32_e32 v9, s3
	ds_write2_b32 v9, v1, v3 offset1:1
	s_waitcnt vmcnt(2)
	v_add_u32_e32 v3, 0xff, v4
	v_add_u32_e32 v1, 0xff, v5
	v_and_b32_e32 v9, 0xffffff00, v3
	v_add_u32_e32 v9, v9, v8
	v_ashrrev_i32_e32 v15, 8, v1
	v_ashrrev_i32_e32 v14, 8, v3
	v_and_b32_e32 v1, 0xffffff00, v1
	v_add_u32_e32 v10, v1, v9
	v_add_u32_e32 v1, v14, v2
	v_add_u32_e32 v3, v15, v1
	s_add_i32 s3, 0, 0x22034
	v_lshlrev_b32_e32 v1, 3, v1
	v_lshlrev_b32_e32 v2, 3, v3
	v_mov_b32_e32 v11, s3
	ds_write2_b32 v11, v1, v2 offset1:1
	v_add_u32_e32 v1, 0xff, v7
	v_add_u32_e32 v2, 0xff, v6
	s_add_i32 s3, 0, 0x220d0
	v_and_b32_e32 v11, 0xffffff00, v2
	v_ashrrev_i32_e32 v17, 8, v1
	v_ashrrev_i32_e32 v16, 8, v2
	v_mov_b32_e32 v2, s3
	s_add_i32 s3, 0, 0x22170
	v_add_u32_e32 v11, v11, v10
	ds_write_b128 v2, v[14:17]
	v_mov_b32_e32 v2, s3
	s_add_i32 s3, 0, 0x22210
	ds_write_b128 v2, v[8:11]
	v_mov_b32_e32 v2, s3
	v_and_b32_e32 v1, 0xffffff00, v1
	ds_write_b128 v2, v[4:7]
	v_add_u32_e32 v2, v1, v11
	v_add_u32_e32 v1, v16, v3
	v_add_u32_e32 v5, v17, v1
	global_load_dwordx4 v[6:9], v0, s[6:7] offset:112
	global_load_dwordx4 v[14:17], v0, s[6:7] offset:96
	s_add_i32 s3, 0, 0x2203c
	v_lshlrev_b32_e32 v1, 3, v1
	v_lshlrev_b32_e32 v3, 3, v5
	v_mov_b32_e32 v4, s3
	ds_write2_b32 v4, v1, v3 offset1:1
	s_waitcnt vmcnt(2)
	v_add_u32_e32 v1, 0xff, v26
	v_add_u32_e32 v0, 0xff, v27
	v_and_b32_e32 v3, 0xffffff00, v1
	v_add_u32_e32 v3, v3, v2
	v_ashrrev_i32_e32 v19, 8, v0
	v_ashrrev_i32_e32 v18, 8, v1
	v_and_b32_e32 v0, 0xffffff00, v0
	v_add_u32_e32 v4, v0, v3
	v_add_u32_e32 v0, v18, v5
	v_add_u32_e32 v1, v19, v0
	s_add_i32 s3, 0, 0x22044
	v_lshlrev_b32_e32 v0, 3, v0
	v_lshlrev_b32_e32 v5, 3, v1
	v_mov_b32_e32 v10, s3
	ds_write2_b32 v10, v0, v5 offset1:1
	v_add_u32_e32 v0, 0xff, v29
	v_add_u32_e32 v10, 0xff, v28
	s_add_i32 s3, 0, 0x220e0
	v_and_b32_e32 v5, 0xffffff00, v10
	v_ashrrev_i32_e32 v21, 8, v0
	v_ashrrev_i32_e32 v20, 8, v10
	v_mov_b32_e32 v10, s3
	s_add_i32 s3, 0, 0x22180
	v_add_u32_e32 v5, v5, v4
	ds_write_b128 v10, v[18:21]
	v_mov_b32_e32 v10, s3
	s_add_i32 s3, 0, 0x22220
	v_add_u32_e32 v1, v20, v1
	ds_write_b128 v10, v[2:5]
	v_mov_b32_e32 v2, s3
	v_add_u32_e32 v3, v21, v1
	s_add_i32 s3, 0, 0x2204c
	ds_write_b128 v2, v[26:29]
	v_lshlrev_b32_e32 v1, 3, v1
	v_lshlrev_b32_e32 v2, 3, v3
	v_mov_b32_e32 v4, s3
	ds_write2_b32 v4, v1, v2 offset1:1
	v_add_u32_e32 v4, 0xff, v22
	v_add_u32_e32 v2, 0xff, v23
	v_ashrrev_i32_e32 v18, 8, v4
	v_ashrrev_i32_e32 v19, 8, v2
	v_add_u32_e32 v3, v18, v3
	v_and_b32_e32 v0, 0xffffff00, v0
	v_and_b32_e32 v1, 0xffffff00, v4
	v_add_u32_e32 v4, v19, v3
	s_add_i32 s3, 0, 0x22054
	v_add_u32_e32 v0, v0, v5
	v_lshlrev_b32_e32 v3, 3, v3
	v_lshlrev_b32_e32 v5, 3, v4
	v_mov_b32_e32 v10, s3
	v_add_u32_e32 v1, v1, v0
	v_and_b32_e32 v2, 0xffffff00, v2
	ds_write2_b32 v10, v3, v5 offset1:1
	v_add_u32_e32 v5, 0xff, v25
	v_add_u32_e32 v10, 0xff, v24
	s_add_i32 s3, 0, 0x220f0
	v_add_u32_e32 v2, v2, v1
	v_and_b32_e32 v3, 0xffffff00, v10
	v_ashrrev_i32_e32 v21, 8, v5
	v_ashrrev_i32_e32 v20, 8, v10
	v_mov_b32_e32 v10, s3
	s_add_i32 s3, 0, 0x22190
	v_add_u32_e32 v3, v3, v2
	ds_write_b128 v10, v[18:21]
	v_mov_b32_e32 v10, s3
	s_add_i32 s3, 0, 0x22230
	ds_write_b128 v10, v[0:3]
	v_mov_b32_e32 v0, s3
	ds_write_b128 v0, v[22:25]
	v_and_b32_e32 v0, 0xffffff00, v5
	v_add_u32_e32 v1, v20, v4
	v_add_u32_e32 v0, v0, v3
	v_add_u32_e32 v3, v21, v1
	s_add_i32 s3, 0, 0x2205c
	v_lshlrev_b32_e32 v1, 3, v1
	v_lshlrev_b32_e32 v2, 3, v3
	v_mov_b32_e32 v4, s3
	ds_write2_b32 v4, v1, v2 offset1:1
	s_waitcnt vmcnt(0)
	v_add_u32_e32 v4, 0xff, v14
	v_add_u32_e32 v2, 0xff, v15
	v_ashrrev_i32_e32 v18, 8, v4
	v_ashrrev_i32_e32 v19, 8, v2
	v_add_u32_e32 v3, v18, v3
	v_and_b32_e32 v1, 0xffffff00, v4
	v_add_u32_e32 v4, v19, v3
	s_add_i32 s3, 0, 0x22064
	v_lshlrev_b32_e32 v3, 3, v3
	v_lshlrev_b32_e32 v5, 3, v4
	v_mov_b32_e32 v10, s3
	v_add_u32_e32 v1, v1, v0
	v_and_b32_e32 v2, 0xffffff00, v2
	ds_write2_b32 v10, v3, v5 offset1:1
	v_add_u32_e32 v5, 0xff, v17
	v_add_u32_e32 v10, 0xff, v16
	s_add_i32 s3, 0, 0x22100
	v_add_u32_e32 v2, v2, v1
	v_and_b32_e32 v3, 0xffffff00, v10
	v_ashrrev_i32_e32 v21, 8, v5
	v_ashrrev_i32_e32 v20, 8, v10
	v_mov_b32_e32 v10, s3
	s_add_i32 s3, 0, 0x221a0
	v_add_u32_e32 v3, v3, v2
	ds_write_b128 v10, v[18:21]
	v_mov_b32_e32 v10, s3
	s_add_i32 s3, 0, 0x22240
	ds_write_b128 v10, v[0:3]
	v_mov_b32_e32 v0, s3
	ds_write_b128 v0, v[14:17]
	v_and_b32_e32 v0, 0xffffff00, v5
	v_add_u32_e32 v1, v20, v4
	v_add_u32_e32 v0, v0, v3
	v_add_u32_e32 v3, v21, v1
	s_add_i32 s3, 0, 0x2206c
	v_lshlrev_b32_e32 v1, 3, v1
	v_lshlrev_b32_e32 v2, 3, v3
	v_mov_b32_e32 v4, s3
	ds_write2_b32 v4, v1, v2 offset1:1
	v_add_u32_e32 v4, 0xff, v6
	v_add_u32_e32 v2, 0xff, v7
	v_ashrrev_i32_e32 v14, 8, v4
	v_ashrrev_i32_e32 v15, 8, v2
	v_add_u32_e32 v3, v14, v3
	v_and_b32_e32 v1, 0xffffff00, v4
	v_add_u32_e32 v4, v15, v3
	s_add_i32 s3, 0, 0x22074
	v_lshlrev_b32_e32 v3, 3, v3
	v_lshlrev_b32_e32 v5, 3, v4
	v_mov_b32_e32 v10, s3
	v_add_u32_e32 v1, v1, v0
	v_and_b32_e32 v2, 0xffffff00, v2
	ds_write2_b32 v10, v3, v5 offset1:1
	v_add_u32_e32 v5, 0xff, v9
	v_add_u32_e32 v10, 0xff, v8
	s_add_i32 s3, 0, 0x22110
	v_add_u32_e32 v2, v2, v1
	v_and_b32_e32 v3, 0xffffff00, v10
	v_ashrrev_i32_e32 v17, 8, v5
	v_ashrrev_i32_e32 v16, 8, v10
	v_mov_b32_e32 v5, s3
	s_add_i32 s3, 0, 0x221b0
	v_add_u32_e32 v3, v3, v2
	ds_write_b128 v5, v[14:17]
	v_mov_b32_e32 v5, s3
	s_add_i32 s3, 0, 0x22250
	ds_write_b128 v5, v[0:3]
	v_mov_b32_e32 v0, s3
	ds_write_b128 v0, v[6:9]
	v_add_u32_e32 v0, v16, v4
	v_add_u32_e32 v1, v17, v0
	s_add_i32 s3, 0, 0x2207c
	v_lshlrev_b32_e32 v0, 3, v0
	v_lshlrev_b32_e32 v1, 3, v1
	v_mov_b32_e32 v2, s3
	ds_write2_b32 v2, v0, v1 offset1:1

.LBB0_2400:
	v_mov_b32_e32 v180, v209
	s_nop 0
	v_ashrrev_i32_e32 v182, 31, v180
	v_lshrrev_b32_e32 v182, 26, v182
	v_lshlrev_b32_e32 v184, 4, v180
	v_add_u32_e32 v182, v180, v182
	v_bfe_i32 v180, v180, 27, 1
	v_lshrrev_b32_e32 v180, 22, v180
	v_add_u32_e32 v180, v184, v180
	v_and_b32_e32 v180, 0xfffffc00, v180
	v_sub_u32_e32 v180, v184, v180
	v_add_u32_e32 v184, 0x2000, v184
	v_ashrrev_i32_e32 v185, 31, v184
	v_lshrrev_b32_e32 v185, 22, v185
	v_add_u32_e32 v185, v184, v185
	v_ashrrev_i32_e32 v208, 10, v185
	v_mul_i32_i24_e32 v185, 0x400, v208
	v_ashrrev_i32_e32 v206, 6, v182
	v_lshrrev_b32_e32 v182, 4, v180
	v_sub_u32_e32 v184, v184, v185
	v_bitop3_b32 v180, v182, v180, 32 bitop3:0x6c
	v_lshrrev_b32_e32 v185, 4, v184
	v_ashrrev_i32_e32 v183, 31, v180
	v_bitop3_b32 v215, v185, v184, 32 bitop3:0x6c
	v_lshrrev_b32_e32 v183, 26, v183
	v_ashrrev_i32_e32 v185, 31, v215
	v_lshlrev_b32_e32 v182, 3, v206
	v_add_u32_e32 v207, v180, v183
	v_lshrrev_b32_e32 v185, 26, v185
	v_and_b32_e32 v182, -16, v182
	v_ashrrev_i32_e32 v183, 6, v207
	v_lshlrev_b32_e32 v184, 3, v208
	v_add_u32_e32 v216, v215, v185
	v_add_u32_e32 v186, v183, v182
	v_and_b32_e32 v184, -16, v184
	v_ashrrev_i32_e32 v185, 6, v216
	v_min_i32_e32 v182, v186, v214
	v_add_u32_e32 v204, v185, v184
	v_add_u32_e32 v186, 0x80, v186
	v_min_i32_e32 v184, v204, v214
	v_min_i32_e32 v186, v186, v214
	v_add_u32_e32 v204, 0x80, v204
	v_ashrrev_i32_e32 v183, 31, v182
	v_ashrrev_i32_e32 v185, 31, v184
	v_ashrrev_i32_e32 v187, 31, v186
	v_min_i32_e32 v204, v204, v214
	v_lshl_add_u64 v[182:183], v[182:183], 2, v[190:191]
	v_lshl_add_u64 v[184:185], v[184:185], 2, v[190:191]
	v_lshl_add_u64 v[186:187], v[186:187], 2, v[190:191]
	v_ashrrev_i32_e32 v205, 31, v204
	v_lshl_add_u64 v[204:205], v[204:205], 2, v[190:191]
	v_mov_b32_e32 v182, v242
	s_nop 0
	v_mov_b32_e32 v184, v244
	s_nop 0
	v_mov_b32_e32 v185, v245
	s_nop 0
	v_mov_b32_e32 v186, v246
	v_and_b32_e32 v205, 0xc0, v207
	v_sub_u32_e32 v180, v180, v205
	v_lshlrev_b32_e32 v187, 5, v206
	v_ashrrev_i16_sdwa v180, v199, sext(v180) dst_sel:DWORD dst_unused:UNUSED_PAD src0_sel:DWORD src1_sel:BYTE_0
	v_and_b32_e32 v187, 32, v187
	v_bfe_i32 v180, v180, 0, 16
	v_and_b32_e32 v205, 0xc0, v216
	v_add_lshl_u32 v180, v187, v180, 1
	v_sub_u32_e32 v187, v215, v205
	v_lshlrev_b32_e32 v204, 5, v208
	v_ashrrev_i16_sdwa v187, v199, sext(v187) dst_sel:DWORD dst_unused:UNUSED_PAD src0_sel:DWORD src1_sel:BYTE_0
	v_and_b32_e32 v204, 32, v204
	v_bfe_i32 v187, v187, 0, 16
	v_add_lshl_u32 v187, v204, v187, 1
	v_mov_b32_e32 v183, v181
	v_lshl_add_u32 v206, v182, 12, v180
	v_lshl_add_u32 v184, v184, 12, v187
	v_lshl_add_u32 v180, v185, 12, v180
	v_lshl_add_u32 v182, v186, 12, v187
	v_mov_b64_e32 v[204:205], v[180:181]
	v_mov_b32_e32 v186, v180
	v_mov_b32_e32 v180, v206

.LBB0_2459:
	s_cmp_gt_i32 s40, 19
	s_cselect_b64 s[4:5], -1, 0
	s_cmp_lt_i32 s41, 20
	s_cselect_b64 s[6:7], -1, 0
	s_or_b64 s[4:5], s[4:5], s[6:7]
	s_and_b64 vcc, exec, s[4:5]
	s_cbranch_vccnz .LBB0_2540
	s_waitcnt vmcnt(0)
	v_mbcnt_lo_u32_b32 v0, -1, 0
	v_mbcnt_hi_u32_b32 v12, -1, v0
	v_add_u32_e32 v13, s63, v12
	s_mov_b64 s[4:5], s[0:1]
	v_cmp_eq_u32_e32 vcc, 0, v13
	s_waitcnt lgkmcnt(0)
	s_barrier
	s_cmp_le_i32 s40, 18
	s_cselect_b64 s[6:7], 0, -1
	s_and_b64 vcc, vcc, s[6:7]
	s_and_saveexec_b64 s[6:7], vcc
	s_cbranch_execz .LBB0_2462
	s_load_dwordx2 s[8:9], s[4:5], 0x178
	v_mov_b32_e32 v0, 0
	s_add_i32 s12, 0, 0x221e0
	v_mov_b32_e32 v1, s12
	s_add_i32 s10, 0, 0x220a0
	s_waitcnt lgkmcnt(0)
	global_load_dwordx4 v[14:17], v0, s[8:9] offset:128
	global_load_dwordx4 v[18:21], v0, s[8:9] offset:144
	global_load_dwordx4 v[8:11], v0, s[8:9] offset:160
	global_load_dwordx4 v[4:7], v0, s[8:9] offset:176
	s_add_i32 s17, 0, 0x221f0
	global_load_dwordx4 v[22:25], v0, s[8:9] offset:208
	global_load_dwordx4 v[26:29], v0, s[8:9] offset:192
	s_add_i32 s3, 0, 0x22000
	s_add_i32 s15, 0, 0x220b0
	v_mov_b32_e32 v2, s10
	v_mov_b32_e32 v30, s17
	s_add_i32 s11, 0, 0x22140
	v_mov_b32_e32 v32, s3
	v_mov_b32_e32 v3, s15
	s_add_i32 s13, 0, 0x2200c
	v_mov_b32_e32 v33, s11
	v_mov_b32_e32 v34, s13
	s_add_i32 s14, 0, 0x22014
	s_add_i32 s16, 0, 0x22150
	v_mov_b32_e32 v35, s14
	s_add_i32 s18, 0, 0x2201c
	v_mov_b32_e32 v36, s16
	v_mov_b32_e32 v37, s18
	s_add_i32 s3, 0, 0x22024
	s_waitcnt vmcnt(5)
	v_add_u32_e32 v31, 0xff, v15
	v_add_u32_e32 v38, 0xff, v14
	v_add_u32_e32 v39, 0xff, v17
	v_add_u32_e32 v40, 0xff, v16
	ds_write_b128 v1, v[14:17]
	v_ashrrev_i32_e32 v14, 8, v38
	v_ashrrev_i32_e32 v15, 8, v31
	s_waitcnt vmcnt(4)
	v_add_u32_e32 v1, 0xff, v19
	v_add_u32_e32 v41, 0xff, v18
	v_add_u32_e32 v42, 0xff, v21
	v_add_u32_e32 v43, 0xff, v20
	v_and_b32_e32 v45, 0xffffff00, v38
	v_and_b32_e32 v38, 0xffffff00, v31
	v_ashrrev_i32_e32 v17, 8, v39
	v_ashrrev_i32_e32 v16, 8, v40
	v_add_u32_e32 v48, v15, v14
	ds_write_b128 v30, v[18:21]
	v_and_b32_e32 v46, 0xffffff00, v40
	v_and_b32_e32 v40, 0xffffff00, v41
	v_ashrrev_i32_e32 v19, 8, v1
	v_ashrrev_i32_e32 v18, 8, v41
	v_and_b32_e32 v41, 0xffffff00, v1
	v_ashrrev_i32_e32 v21, 8, v42
	v_ashrrev_i32_e32 v20, 8, v43
	v_add_u32_e32 v38, v38, v45
	v_lshlrev_b32_e32 v1, 3, v14
	ds_write_b128 v2, v[14:17]
	ds_write_b128 v3, v[18:21]
	v_lshlrev_b32_e32 v2, 3, v48
	v_add_u32_e32 v15, v16, v48
	v_and_b32_e32 v39, 0xffffff00, v39
	v_add_u32_e32 v3, v46, v38
	ds_write_b96 v32, v[0:2]
	v_mov_b32_e32 v1, v45
	v_mov_b32_e32 v2, v38
	v_add_u32_e32 v16, v17, v15
	v_add_u32_e32 v14, v39, v3
	v_lshlrev_b32_e32 v17, 3, v15
	ds_write_b128 v33, v[0:3]
	v_lshlrev_b32_e32 v1, 3, v16
	v_add_u32_e32 v2, v18, v16
	v_add_u32_e32 v15, v40, v14
	ds_write2_b32 v34, v17, v1 offset1:1
	v_add_u32_e32 v1, v19, v2
	s_waitcnt vmcnt(3)
	v_add_u32_e32 v30, 0xff, v8
	v_and_b32_e32 v47, 0xffffff00, v43
	v_add_u32_e32 v16, v41, v15
	v_lshlrev_b32_e32 v2, 3, v2
	v_lshlrev_b32_e32 v3, 3, v1
	v_add_u32_e32 v1, v20, v1
	v_add_u32_e32 v44, 0xff, v9
	v_and_b32_e32 v43, 0xffffff00, v30
	v_ashrrev_i32_e32 v30, 8, v30
	v_add_u32_e32 v17, v47, v16
	ds_write2_b32 v35, v2, v3 offset1:1
	ds_write_b128 v36, v[14:17]
	v_add_u32_e32 v2, v21, v1
	v_ashrrev_i32_e32 v31, 8, v44
	v_lshlrev_b32_e32 v1, 3, v1
	v_lshlrev_b32_e32 v3, 3, v2
	v_add_u32_e32 v2, v30, v2
	v_and_b32_e32 v42, 0xffffff00, v42
	ds_write2_b32 v37, v1, v3 offset1:1
	v_add_u32_e32 v1, v31, v2
	v_add_u32_e32 v14, v42, v17
	v_lshlrev_b32_e32 v2, 3, v2
	v_lshlrev_b32_e32 v3, 3, v1
	v_mov_b32_e32 v17, s3
	v_and_b32_e32 v44, 0xffffff00, v44
	v_add_u32_e32 v15, v43, v14
	ds_write2_b32 v17, v2, v3 offset1:1
	v_add_u32_e32 v2, 0xff, v11
	v_add_u32_e32 v3, 0xff, v10
	s_add_i32 s3, 0, 0x220c0
	v_add_u32_e32 v16, v44, v15
	v_and_b32_e32 v17, 0xffffff00, v3
	v_ashrrev_i32_e32 v33, 8, v2
	v_ashrrev_i32_e32 v32, 8, v3
	v_mov_b32_e32 v3, s3
	s_add_i32 s3, 0, 0x22160
	v_add_u32_e32 v17, v17, v16
	ds_write_b128 v3, v[30:33]
	v_mov_b32_e32 v3, s3
	s_add_i32 s3, 0, 0x22200
	ds_write_b128 v3, v[14:17]
	v_mov_b32_e32 v3, s3
	v_and_b32_e32 v2, 0xffffff00, v2
	v_add_u32_e32 v1, v32, v1
	ds_write_b128 v3, v[8:11]
	v_add_u32_e32 v8, v2, v17
	v_add_u32_e32 v2, v33, v1
	s_add_i32 s3, 0, 0x2202c
	v_lshlrev_b32_e32 v1, 3, v1
	v_lshlrev_b32_e32 v3, 3, v2
	v_mov_b32_e32 v9, s3
	ds_write2_b32 v9, v1, v3 offset1:1
	s_waitcnt vmcnt(2)
	v_add_u32_e32 v3, 0xff, v4
	v_add_u32_e32 v1, 0xff, v5
	v_and_b32_e32 v9, 0xffffff00, v3
	v_add_u32_e32 v9, v9, v8
	v_ashrrev_i32_e32 v15, 8, v1
	v_ashrrev_i32_e32 v14, 8, v3
	v_and_b32_e32 v1, 0xffffff00, v1
	v_add_u32_e32 v10, v1, v9
	v_add_u32_e32 v1, v14, v2
	v_add_u32_e32 v3, v15, v1
	s_add_i32 s3, 0, 0x22034
	v_lshlrev_b32_e32 v1, 3, v1
	v_lshlrev_b32_e32 v2, 3, v3
	v_mov_b32_e32 v11, s3
	ds_write2_b32 v11, v1, v2 offset1:1
	v_add_u32_e32 v1, 0xff, v7
	v_add_u32_e32 v2, 0xff, v6
	s_add_i32 s3, 0, 0x220d0
	v_and_b32_e32 v11, 0xffffff00, v2
	v_ashrrev_i32_e32 v17, 8, v1
	v_ashrrev_i32_e32 v16, 8, v2
	v_mov_b32_e32 v2, s3
	s_add_i32 s3, 0, 0x22170
	v_add_u32_e32 v11, v11, v10
	ds_write_b128 v2, v[14:17]
	v_mov_b32_e32 v2, s3
	s_add_i32 s3, 0, 0x22210
	ds_write_b128 v2, v[8:11]
	v_mov_b32_e32 v2, s3
	v_and_b32_e32 v1, 0xffffff00, v1
	ds_write_b128 v2, v[4:7]
	v_add_u32_e32 v2, v1, v11
	v_add_u32_e32 v1, v16, v3
	v_add_u32_e32 v5, v17, v1
	global_load_dwordx4 v[6:9], v0, s[8:9] offset:240
	global_load_dwordx4 v[14:17], v0, s[8:9] offset:224
	s_add_i32 s3, 0, 0x2203c
	v_lshlrev_b32_e32 v1, 3, v1
	v_lshlrev_b32_e32 v3, 3, v5
	v_mov_b32_e32 v4, s3
	ds_write2_b32 v4, v1, v3 offset1:1
	s_waitcnt vmcnt(2)
	v_add_u32_e32 v1, 0xff, v26
	v_add_u32_e32 v0, 0xff, v27
	v_and_b32_e32 v3, 0xffffff00, v1
	v_add_u32_e32 v3, v3, v2
	v_ashrrev_i32_e32 v19, 8, v0
	v_ashrrev_i32_e32 v18, 8, v1
	v_and_b32_e32 v0, 0xffffff00, v0
	v_add_u32_e32 v4, v0, v3
	v_add_u32_e32 v0, v18, v5
	v_add_u32_e32 v1, v19, v0
	s_add_i32 s3, 0, 0x22044
	v_lshlrev_b32_e32 v0, 3, v0
	v_lshlrev_b32_e32 v5, 3, v1
	v_mov_b32_e32 v10, s3
	ds_write2_b32 v10, v0, v5 offset1:1
	v_add_u32_e32 v0, 0xff, v29
	v_add_u32_e32 v10, 0xff, v28
	s_add_i32 s3, 0, 0x220e0
	v_and_b32_e32 v5, 0xffffff00, v10
	v_ashrrev_i32_e32 v21, 8, v0
	v_ashrrev_i32_e32 v20, 8, v10
	v_mov_b32_e32 v10, s3
	s_add_i32 s3, 0, 0x22180
	v_add_u32_e32 v5, v5, v4
	ds_write_b128 v10, v[18:21]
	v_mov_b32_e32 v10, s3
	s_add_i32 s3, 0, 0x22220
	v_add_u32_e32 v1, v20, v1
	ds_write_b128 v10, v[2:5]
	v_mov_b32_e32 v2, s3
	v_add_u32_e32 v3, v21, v1
	s_add_i32 s3, 0, 0x2204c
	ds_write_b128 v2, v[26:29]
	v_lshlrev_b32_e32 v1, 3, v1
	v_lshlrev_b32_e32 v2, 3, v3
	v_mov_b32_e32 v4, s3
	ds_write2_b32 v4, v1, v2 offset1:1
	v_add_u32_e32 v4, 0xff, v22
	v_add_u32_e32 v2, 0xff, v23
	v_ashrrev_i32_e32 v18, 8, v4
	v_ashrrev_i32_e32 v19, 8, v2
	v_add_u32_e32 v3, v18, v3
	v_and_b32_e32 v0, 0xffffff00, v0
	v_and_b32_e32 v1, 0xffffff00, v4
	v_add_u32_e32 v4, v19, v3
	s_add_i32 s3, 0, 0x22054
	v_add_u32_e32 v0, v0, v5
	v_lshlrev_b32_e32 v3, 3, v3
	v_lshlrev_b32_e32 v5, 3, v4
	v_mov_b32_e32 v10, s3
	v_add_u32_e32 v1, v1, v0
	v_and_b32_e32 v2, 0xffffff00, v2
	ds_write2_b32 v10, v3, v5 offset1:1
	v_add_u32_e32 v5, 0xff, v25
	v_add_u32_e32 v10, 0xff, v24
	s_add_i32 s3, 0, 0x220f0
	v_add_u32_e32 v2, v2, v1
	v_and_b32_e32 v3, 0xffffff00, v10
	v_ashrrev_i32_e32 v21, 8, v5
	v_ashrrev_i32_e32 v20, 8, v10
	v_mov_b32_e32 v10, s3
	s_add_i32 s3, 0, 0x22190
	v_add_u32_e32 v3, v3, v2
	ds_write_b128 v10, v[18:21]
	v_mov_b32_e32 v10, s3
	s_add_i32 s3, 0, 0x22230
	ds_write_b128 v10, v[0:3]
	v_mov_b32_e32 v0, s3
	ds_write_b128 v0, v[22:25]
	v_and_b32_e32 v0, 0xffffff00, v5
	v_add_u32_e32 v1, v20, v4
	v_add_u32_e32 v0, v0, v3
	v_add_u32_e32 v3, v21, v1
	s_add_i32 s3, 0, 0x2205c
	v_lshlrev_b32_e32 v1, 3, v1
	v_lshlrev_b32_e32 v2, 3, v3
	v_mov_b32_e32 v4, s3
	ds_write2_b32 v4, v1, v2 offset1:1
	s_waitcnt vmcnt(0)
	v_add_u32_e32 v4, 0xff, v14
	v_add_u32_e32 v2, 0xff, v15
	v_ashrrev_i32_e32 v18, 8, v4
	v_ashrrev_i32_e32 v19, 8, v2
	v_add_u32_e32 v3, v18, v3
	v_and_b32_e32 v1, 0xffffff00, v4
	v_add_u32_e32 v4, v19, v3
	s_add_i32 s3, 0, 0x22064
	v_lshlrev_b32_e32 v3, 3, v3
	v_lshlrev_b32_e32 v5, 3, v4
	v_mov_b32_e32 v10, s3
	v_add_u32_e32 v1, v1, v0
	v_and_b32_e32 v2, 0xffffff00, v2
	ds_write2_b32 v10, v3, v5 offset1:1
	v_add_u32_e32 v5, 0xff, v17
	v_add_u32_e32 v10, 0xff, v16
	s_add_i32 s3, 0, 0x22100
	v_add_u32_e32 v2, v2, v1
	v_and_b32_e32 v3, 0xffffff00, v10
	v_ashrrev_i32_e32 v21, 8, v5
	v_ashrrev_i32_e32 v20, 8, v10
	v_mov_b32_e32 v10, s3
	s_add_i32 s3, 0, 0x221a0
	v_add_u32_e32 v3, v3, v2
	ds_write_b128 v10, v[18:21]
	v_mov_b32_e32 v10, s3
	s_add_i32 s3, 0, 0x22240
	ds_write_b128 v10, v[0:3]
	v_mov_b32_e32 v0, s3
	ds_write_b128 v0, v[14:17]
	v_and_b32_e32 v0, 0xffffff00, v5
	v_add_u32_e32 v1, v20, v4
	v_add_u32_e32 v0, v0, v3
	v_add_u32_e32 v3, v21, v1
	s_add_i32 s3, 0, 0x2206c
	v_lshlrev_b32_e32 v1, 3, v1
	v_lshlrev_b32_e32 v2, 3, v3
	v_mov_b32_e32 v4, s3
	ds_write2_b32 v4, v1, v2 offset1:1
	v_add_u32_e32 v4, 0xff, v6
	v_add_u32_e32 v2, 0xff, v7
	v_ashrrev_i32_e32 v14, 8, v4
	v_ashrrev_i32_e32 v15, 8, v2
	v_add_u32_e32 v3, v14, v3
	v_and_b32_e32 v1, 0xffffff00, v4
	v_add_u32_e32 v4, v15, v3
	s_add_i32 s3, 0, 0x22074
	v_lshlrev_b32_e32 v3, 3, v3
	v_lshlrev_b32_e32 v5, 3, v4
	v_mov_b32_e32 v10, s3
	v_add_u32_e32 v1, v1, v0
	v_and_b32_e32 v2, 0xffffff00, v2
	ds_write2_b32 v10, v3, v5 offset1:1
	v_add_u32_e32 v5, 0xff, v9
	v_add_u32_e32 v10, 0xff, v8
	s_add_i32 s3, 0, 0x22110
	v_add_u32_e32 v2, v2, v1
	v_and_b32_e32 v3, 0xffffff00, v10
	v_ashrrev_i32_e32 v17, 8, v5
	v_ashrrev_i32_e32 v16, 8, v10
	v_mov_b32_e32 v5, s3
	s_add_i32 s3, 0, 0x221b0
	v_add_u32_e32 v3, v3, v2
	ds_write_b128 v5, v[14:17]
	v_mov_b32_e32 v5, s3
	s_add_i32 s3, 0, 0x22250
	ds_write_b128 v5, v[0:3]
	v_mov_b32_e32 v0, s3
	ds_write_b128 v0, v[6:9]
	v_add_u32_e32 v0, v16, v4
	v_add_u32_e32 v1, v17, v0
	s_add_i32 s3, 0, 0x2207c
	v_lshlrev_b32_e32 v0, 3, v0
	v_lshlrev_b32_e32 v1, 3, v1
	v_mov_b32_e32 v2, s3
	ds_write2_b32 v2, v0, v1 offset1:1

.LBB0_2540:
	s_cmp_gt_i32 s40, 20
	s_cselect_b64 s[4:5], -1, 0
	s_cmp_lt_i32 s41, 21
	s_cselect_b64 s[6:7], -1, 0
	s_or_b64 s[4:5], s[4:5], s[6:7]
	s_and_b64 vcc, exec, s[4:5]
	s_cbranch_vccnz .LBB0_2598
	s_waitcnt vmcnt(0)
	v_mbcnt_lo_u32_b32 v0, -1, 0
	v_mbcnt_hi_u32_b32 v12, -1, v0
	v_add_u32_e32 v13, s63, v12
	s_mov_b64 s[4:5], s[0:1]
	v_cmp_eq_u32_e32 vcc, 0, v13
	s_waitcnt lgkmcnt(0)
	s_barrier
	s_cmp_le_i32 s40, 18
	s_cselect_b64 s[6:7], 0, -1
	s_and_b64 vcc, vcc, s[6:7]
	s_and_saveexec_b64 s[6:7], vcc
	s_cbranch_execz .LBB0_2543
	s_load_dwordx2 s[8:9], s[4:5], 0x178
	v_mov_b32_e32 v0, 0
	s_add_i32 s12, 0, 0x221e0
	v_mov_b32_e32 v1, s12
	s_add_i32 s10, 0, 0x220a0
	s_waitcnt lgkmcnt(0)
	global_load_dwordx4 v[14:17], v0, s[8:9] offset:128
	global_load_dwordx4 v[18:21], v0, s[8:9] offset:144
	global_load_dwordx4 v[8:11], v0, s[8:9] offset:160
	global_load_dwordx4 v[4:7], v0, s[8:9] offset:176
	s_add_i32 s17, 0, 0x221f0
	global_load_dwordx4 v[22:25], v0, s[8:9] offset:208
	global_load_dwordx4 v[26:29], v0, s[8:9] offset:192
	s_add_i32 s3, 0, 0x22000
	s_add_i32 s15, 0, 0x220b0
	v_mov_b32_e32 v2, s10
	v_mov_b32_e32 v30, s17
	s_add_i32 s11, 0, 0x22140
	v_mov_b32_e32 v32, s3
	v_mov_b32_e32 v3, s15
	s_add_i32 s13, 0, 0x2200c
	v_mov_b32_e32 v33, s11
	v_mov_b32_e32 v34, s13
	s_add_i32 s14, 0, 0x22014
	s_add_i32 s16, 0, 0x22150
	v_mov_b32_e32 v35, s14
	s_add_i32 s18, 0, 0x2201c
	v_mov_b32_e32 v36, s16
	v_mov_b32_e32 v37, s18
	s_add_i32 s3, 0, 0x22024
	s_waitcnt vmcnt(5)
	v_add_u32_e32 v31, 0xff, v15
	v_add_u32_e32 v38, 0xff, v14
	v_add_u32_e32 v39, 0xff, v17
	v_add_u32_e32 v40, 0xff, v16
	ds_write_b128 v1, v[14:17]
	v_ashrrev_i32_e32 v14, 8, v38
	v_ashrrev_i32_e32 v15, 8, v31
	s_waitcnt vmcnt(4)
	v_add_u32_e32 v1, 0xff, v19
	v_add_u32_e32 v41, 0xff, v18
	v_add_u32_e32 v42, 0xff, v21
	v_add_u32_e32 v43, 0xff, v20
	v_and_b32_e32 v45, 0xffffff00, v38
	v_and_b32_e32 v38, 0xffffff00, v31
	v_ashrrev_i32_e32 v17, 8, v39
	v_ashrrev_i32_e32 v16, 8, v40
	v_add_u32_e32 v48, v15, v14
	ds_write_b128 v30, v[18:21]
	v_and_b32_e32 v46, 0xffffff00, v40
	v_and_b32_e32 v40, 0xffffff00, v41
	v_ashrrev_i32_e32 v19, 8, v1
	v_ashrrev_i32_e32 v18, 8, v41
	v_and_b32_e32 v41, 0xffffff00, v1
	v_ashrrev_i32_e32 v21, 8, v42
	v_ashrrev_i32_e32 v20, 8, v43
	v_add_u32_e32 v38, v38, v45
	v_lshlrev_b32_e32 v1, 3, v14
	ds_write_b128 v2, v[14:17]
	ds_write_b128 v3, v[18:21]
	v_lshlrev_b32_e32 v2, 3, v48
	v_add_u32_e32 v15, v16, v48
	v_and_b32_e32 v39, 0xffffff00, v39
	v_add_u32_e32 v3, v46, v38
	ds_write_b96 v32, v[0:2]
	v_mov_b32_e32 v1, v45
	v_mov_b32_e32 v2, v38
	v_add_u32_e32 v16, v17, v15
	v_add_u32_e32 v14, v39, v3
	v_lshlrev_b32_e32 v17, 3, v15
	ds_write_b128 v33, v[0:3]
	v_lshlrev_b32_e32 v1, 3, v16
	v_add_u32_e32 v2, v18, v16
	v_add_u32_e32 v15, v40, v14
	ds_write2_b32 v34, v17, v1 offset1:1
	v_add_u32_e32 v1, v19, v2
	s_waitcnt vmcnt(3)
	v_add_u32_e32 v30, 0xff, v8
	v_and_b32_e32 v47, 0xffffff00, v43
	v_add_u32_e32 v16, v41, v15
	v_lshlrev_b32_e32 v2, 3, v2
	v_lshlrev_b32_e32 v3, 3, v1
	v_add_u32_e32 v1, v20, v1
	v_add_u32_e32 v44, 0xff, v9
	v_and_b32_e32 v43, 0xffffff00, v30
	v_ashrrev_i32_e32 v30, 8, v30
	v_add_u32_e32 v17, v47, v16
	ds_write2_b32 v35, v2, v3 offset1:1
	ds_write_b128 v36, v[14:17]
	v_add_u32_e32 v2, v21, v1
	v_ashrrev_i32_e32 v31, 8, v44
	v_lshlrev_b32_e32 v1, 3, v1
	v_lshlrev_b32_e32 v3, 3, v2
	v_add_u32_e32 v2, v30, v2
	v_and_b32_e32 v42, 0xffffff00, v42
	ds_write2_b32 v37, v1, v3 offset1:1
	v_add_u32_e32 v1, v31, v2
	v_add_u32_e32 v14, v42, v17
	v_lshlrev_b32_e32 v2, 3, v2
	v_lshlrev_b32_e32 v3, 3, v1
	v_mov_b32_e32 v17, s3
	v_and_b32_e32 v44, 0xffffff00, v44
	v_add_u32_e32 v15, v43, v14
	ds_write2_b32 v17, v2, v3 offset1:1
	v_add_u32_e32 v2, 0xff, v11
	v_add_u32_e32 v3, 0xff, v10
	s_add_i32 s3, 0, 0x220c0
	v_add_u32_e32 v16, v44, v15
	v_and_b32_e32 v17, 0xffffff00, v3
	v_ashrrev_i32_e32 v33, 8, v2
	v_ashrrev_i32_e32 v32, 8, v3
	v_mov_b32_e32 v3, s3
	s_add_i32 s3, 0, 0x22160
	v_add_u32_e32 v17, v17, v16
	ds_write_b128 v3, v[30:33]
	v_mov_b32_e32 v3, s3
	s_add_i32 s3, 0, 0x22200
	ds_write_b128 v3, v[14:17]
	v_mov_b32_e32 v3, s3
	v_and_b32_e32 v2, 0xffffff00, v2
	v_add_u32_e32 v1, v32, v1
	ds_write_b128 v3, v[8:11]
	v_add_u32_e32 v8, v2, v17
	v_add_u32_e32 v2, v33, v1
	s_add_i32 s3, 0, 0x2202c
	v_lshlrev_b32_e32 v1, 3, v1
	v_lshlrev_b32_e32 v3, 3, v2
	v_mov_b32_e32 v9, s3
	ds_write2_b32 v9, v1, v3 offset1:1
	s_waitcnt vmcnt(2)
	v_add_u32_e32 v3, 0xff, v4
	v_add_u32_e32 v1, 0xff, v5
	v_and_b32_e32 v9, 0xffffff00, v3
	v_add_u32_e32 v9, v9, v8
	v_ashrrev_i32_e32 v15, 8, v1
	v_ashrrev_i32_e32 v14, 8, v3
	v_and_b32_e32 v1, 0xffffff00, v1
	v_add_u32_e32 v10, v1, v9
	v_add_u32_e32 v1, v14, v2
	v_add_u32_e32 v3, v15, v1
	s_add_i32 s3, 0, 0x22034
	v_lshlrev_b32_e32 v1, 3, v1
	v_lshlrev_b32_e32 v2, 3, v3
	v_mov_b32_e32 v11, s3
	ds_write2_b32 v11, v1, v2 offset1:1
	v_add_u32_e32 v1, 0xff, v7
	v_add_u32_e32 v2, 0xff, v6
	s_add_i32 s3, 0, 0x220d0
	v_and_b32_e32 v11, 0xffffff00, v2
	v_ashrrev_i32_e32 v17, 8, v1
	v_ashrrev_i32_e32 v16, 8, v2
	v_mov_b32_e32 v2, s3
	s_add_i32 s3, 0, 0x22170
	v_add_u32_e32 v11, v11, v10
	ds_write_b128 v2, v[14:17]
	v_mov_b32_e32 v2, s3
	s_add_i32 s3, 0, 0x22210
	ds_write_b128 v2, v[8:11]
	v_mov_b32_e32 v2, s3
	v_and_b32_e32 v1, 0xffffff00, v1
	ds_write_b128 v2, v[4:7]
	v_add_u32_e32 v2, v1, v11
	v_add_u32_e32 v1, v16, v3
	v_add_u32_e32 v5, v17, v1
	global_load_dwordx4 v[6:9], v0, s[8:9] offset:240
	global_load_dwordx4 v[14:17], v0, s[8:9] offset:224
	s_add_i32 s3, 0, 0x2203c
	v_lshlrev_b32_e32 v1, 3, v1
	v_lshlrev_b32_e32 v3, 3, v5
	v_mov_b32_e32 v4, s3
	ds_write2_b32 v4, v1, v3 offset1:1
	s_waitcnt vmcnt(2)
	v_add_u32_e32 v1, 0xff, v26
	v_add_u32_e32 v0, 0xff, v27
	v_and_b32_e32 v3, 0xffffff00, v1
	v_add_u32_e32 v3, v3, v2
	v_ashrrev_i32_e32 v19, 8, v0
	v_ashrrev_i32_e32 v18, 8, v1
	v_and_b32_e32 v0, 0xffffff00, v0
	v_add_u32_e32 v4, v0, v3
	v_add_u32_e32 v0, v18, v5
	v_add_u32_e32 v1, v19, v0
	s_add_i32 s3, 0, 0x22044
	v_lshlrev_b32_e32 v0, 3, v0
	v_lshlrev_b32_e32 v5, 3, v1
	v_mov_b32_e32 v10, s3
	ds_write2_b32 v10, v0, v5 offset1:1
	v_add_u32_e32 v0, 0xff, v29
	v_add_u32_e32 v10, 0xff, v28
	s_add_i32 s3, 0, 0x220e0
	v_and_b32_e32 v5, 0xffffff00, v10
	v_ashrrev_i32_e32 v21, 8, v0
	v_ashrrev_i32_e32 v20, 8, v10
	v_mov_b32_e32 v10, s3
	s_add_i32 s3, 0, 0x22180
	v_add_u32_e32 v5, v5, v4
	ds_write_b128 v10, v[18:21]
	v_mov_b32_e32 v10, s3
	s_add_i32 s3, 0, 0x22220
	v_add_u32_e32 v1, v20, v1
	ds_write_b128 v10, v[2:5]
	v_mov_b32_e32 v2, s3
	v_add_u32_e32 v3, v21, v1
	s_add_i32 s3, 0, 0x2204c
	ds_write_b128 v2, v[26:29]
	v_lshlrev_b32_e32 v1, 3, v1
	v_lshlrev_b32_e32 v2, 3, v3
	v_mov_b32_e32 v4, s3
	ds_write2_b32 v4, v1, v2 offset1:1
	v_add_u32_e32 v4, 0xff, v22
	v_add_u32_e32 v2, 0xff, v23
	v_ashrrev_i32_e32 v18, 8, v4
	v_ashrrev_i32_e32 v19, 8, v2
	v_add_u32_e32 v3, v18, v3
	v_and_b32_e32 v0, 0xffffff00, v0
	v_and_b32_e32 v1, 0xffffff00, v4
	v_add_u32_e32 v4, v19, v3
	s_add_i32 s3, 0, 0x22054
	v_add_u32_e32 v0, v0, v5
	v_lshlrev_b32_e32 v3, 3, v3
	v_lshlrev_b32_e32 v5, 3, v4
	v_mov_b32_e32 v10, s3
	v_add_u32_e32 v1, v1, v0
	v_and_b32_e32 v2, 0xffffff00, v2
	ds_write2_b32 v10, v3, v5 offset1:1
	v_add_u32_e32 v5, 0xff, v25
	v_add_u32_e32 v10, 0xff, v24
	s_add_i32 s3, 0, 0x220f0
	v_add_u32_e32 v2, v2, v1
	v_and_b32_e32 v3, 0xffffff00, v10
	v_ashrrev_i32_e32 v21, 8, v5
	v_ashrrev_i32_e32 v20, 8, v10
	v_mov_b32_e32 v10, s3
	s_add_i32 s3, 0, 0x22190
	v_add_u32_e32 v3, v3, v2
	ds_write_b128 v10, v[18:21]
	v_mov_b32_e32 v10, s3
	s_add_i32 s3, 0, 0x22230
	ds_write_b128 v10, v[0:3]
	v_mov_b32_e32 v0, s3
	ds_write_b128 v0, v[22:25]
	v_and_b32_e32 v0, 0xffffff00, v5
	v_add_u32_e32 v1, v20, v4
	v_add_u32_e32 v0, v0, v3
	v_add_u32_e32 v3, v21, v1
	s_add_i32 s3, 0, 0x2205c
	v_lshlrev_b32_e32 v1, 3, v1
	v_lshlrev_b32_e32 v2, 3, v3
	v_mov_b32_e32 v4, s3
	ds_write2_b32 v4, v1, v2 offset1:1
	s_waitcnt vmcnt(0)
	v_add_u32_e32 v4, 0xff, v14
	v_add_u32_e32 v2, 0xff, v15
	v_ashrrev_i32_e32 v18, 8, v4
	v_ashrrev_i32_e32 v19, 8, v2
	v_add_u32_e32 v3, v18, v3
	v_and_b32_e32 v1, 0xffffff00, v4
	v_add_u32_e32 v4, v19, v3
	s_add_i32 s3, 0, 0x22064
	v_lshlrev_b32_e32 v3, 3, v3
	v_lshlrev_b32_e32 v5, 3, v4
	v_mov_b32_e32 v10, s3
	v_add_u32_e32 v1, v1, v0
	v_and_b32_e32 v2, 0xffffff00, v2
	ds_write2_b32 v10, v3, v5 offset1:1
	v_add_u32_e32 v5, 0xff, v17
	v_add_u32_e32 v10, 0xff, v16
	s_add_i32 s3, 0, 0x22100
	v_add_u32_e32 v2, v2, v1
	v_and_b32_e32 v3, 0xffffff00, v10
	v_ashrrev_i32_e32 v21, 8, v5
	v_ashrrev_i32_e32 v20, 8, v10
	v_mov_b32_e32 v10, s3
	s_add_i32 s3, 0, 0x221a0
	v_add_u32_e32 v3, v3, v2
	ds_write_b128 v10, v[18:21]
	v_mov_b32_e32 v10, s3
	s_add_i32 s3, 0, 0x22240
	ds_write_b128 v10, v[0:3]
	v_mov_b32_e32 v0, s3
	ds_write_b128 v0, v[14:17]
	v_and_b32_e32 v0, 0xffffff00, v5
	v_add_u32_e32 v1, v20, v4
	v_add_u32_e32 v0, v0, v3
	v_add_u32_e32 v3, v21, v1
	s_add_i32 s3, 0, 0x2206c
	v_lshlrev_b32_e32 v1, 3, v1
	v_lshlrev_b32_e32 v2, 3, v3
	v_mov_b32_e32 v4, s3
	ds_write2_b32 v4, v1, v2 offset1:1
	v_add_u32_e32 v4, 0xff, v6
	v_add_u32_e32 v2, 0xff, v7
	v_ashrrev_i32_e32 v14, 8, v4
	v_ashrrev_i32_e32 v15, 8, v2
	v_add_u32_e32 v3, v14, v3
	v_and_b32_e32 v1, 0xffffff00, v4
	v_add_u32_e32 v4, v15, v3
	s_add_i32 s3, 0, 0x22074
	v_lshlrev_b32_e32 v3, 3, v3
	v_lshlrev_b32_e32 v5, 3, v4
	v_mov_b32_e32 v10, s3
	v_add_u32_e32 v1, v1, v0
	v_and_b32_e32 v2, 0xffffff00, v2
	ds_write2_b32 v10, v3, v5 offset1:1
	v_add_u32_e32 v5, 0xff, v9
	v_add_u32_e32 v10, 0xff, v8
	s_add_i32 s3, 0, 0x22110
	v_add_u32_e32 v2, v2, v1
	v_and_b32_e32 v3, 0xffffff00, v10
	v_ashrrev_i32_e32 v17, 8, v5
	v_ashrrev_i32_e32 v16, 8, v10
	v_mov_b32_e32 v5, s3
	s_add_i32 s3, 0, 0x221b0
	v_add_u32_e32 v3, v3, v2
	ds_write_b128 v5, v[14:17]
	v_mov_b32_e32 v5, s3
	s_add_i32 s3, 0, 0x22250
	ds_write_b128 v5, v[0:3]
	v_mov_b32_e32 v0, s3
	ds_write_b128 v0, v[6:9]
	v_add_u32_e32 v0, v16, v4
	v_add_u32_e32 v1, v17, v0
	s_add_i32 s3, 0, 0x2207c
	v_lshlrev_b32_e32 v0, 3, v0
	v_lshlrev_b32_e32 v1, 3, v1
	v_mov_b32_e32 v2, s3
	ds_write2_b32 v2, v0, v1 offset1:1
